# a0post + LDS-DMA issue blocks and pointer increments moved from behind the iteration barrier into step X after the 2nd QK MFMA (post-barrier path = bookkeeping only)
# baseline (speedup 1.0000x reference)
; #define SBAR() __builtin_amdgcn_sched_barrier(0)
; #define ATT_MFMA_SETTLE() asm volatile("s_nop 15\n\ts_nop 15" ::: "memory")
; #define ATT_BAR() asm volatile("s_waitcnt lgkmcnt(0)\n\ts_barrier" ::: "memory")
; #define KLOAD(sl_) k_load_nope(k0, k1, KN_lds + (sl_) * SHM_KN, r32, hi)
; #define WAIT_TILES2() do { if (wid < 4) { ATT_WAITV(6); } else { ATT_WAITV(4); } } while (0)
; __device__ __forceinline__ void attn_unit(const bf16_t* __restrict__ Qb, const unsigned char* __restrict__ Kn, const unsigned char* __restrict__ Vp, const unsigned char* __restrict__ Kp, ...
;     ...
;   KLOAD(0); qk_mma(pA0, pA1, k0, k1, KR_lds, qf, nm, r32, hi, sc); ATT_MFMA_SETTLE(); SBAR(); KLOAD(1); partialSM(pA0, pA1, nm, alA, true);
;   WAIT_TILES2(); ATT_BAR();
;   ISSUE(5, 5 * KVBLK);
;   int s0 = 1;
.LBB0_649:
	s_and_b32 s7, s7, 0x3fffffc0
	s_lshl_b32 s7, s7, 2
	s_add_i32 s7, s7, 0
	v_max_f32_e32 v0, v36, v36
	v_max_f32_e32 v1, v37, v37
	s_add_i32 s7, s7, 0x1e000
	s_add_i32 s57, s8, 0x18000
	v_max_f32_e32 v0, v0, v1
	s_add_u32 s58, s3, s82
	v_add_f32_e32 v0, 0xbfe75768, v0
	s_addc_u32 s59, s72, s83
	v_sub_f32_e32 v115, v35, v0
	v_sub_f32_e32 v114, v34, v0
	v_sub_f32_e32 v113, v33, v0
	v_sub_f32_e32 v112, v32, v0
	v_sub_f32_e32 v111, v31, v0
	v_sub_f32_e32 v110, v30, v0
	v_sub_f32_e32 v109, v29, v0
	v_sub_f32_e32 v108, v28, v0
	v_sub_f32_e32 v107, v27, v0
	v_sub_f32_e32 v106, v26, v0
	v_sub_f32_e32 v105, v25, v0
	v_sub_f32_e32 v104, v24, v0
	v_sub_f32_e32 v103, v23, v0
	v_sub_f32_e32 v102, v22, v0
	v_sub_f32_e32 v101, v21, v0
	v_sub_f32_e32 v100, v20, v0
	v_sub_f32_e32 v99, v19, v0
	v_sub_f32_e32 v98, v18, v0
	v_sub_f32_e32 v97, v17, v0
	v_sub_f32_e32 v96, v16, v0
	v_sub_f32_e32 v95, v15, v0
	v_sub_f32_e32 v94, v14, v0
	v_sub_f32_e32 v93, v13, v0
	v_sub_f32_e32 v92, v12, v0
	v_sub_f32_e32 v91, v11, v0
	v_sub_f32_e32 v90, v10, v0
	v_sub_f32_e32 v89, v9, v0
	v_sub_f32_e32 v88, v8, v0
	v_sub_f32_e32 v87, v7, v0
	v_sub_f32_e32 v86, v6, v0
	v_sub_f32_e32 v85, v5, v0
	v_sub_f32_e32 v84, v4, v0
	v_sub_f32_e32 v68, 0x3fe75768, v0
	v_add_u32_e32 v0, 0, v230
	v_lshl_add_u64 v[210:211], s[58:59], 0, v[2:3]
	s_add_u32 s58, s76, s49
	v_add_u32_e32 v239, v0, v231
	v_add_u32_e32 v240, v0, v232
	s_addc_u32 s59, s77, 0
	s_lshl_b32 s2, s2, 15
	v_lshlrev_b32_e32 v0, 12, v55
	v_or3_b32 v2, s2, v0, v56
	v_lshl_add_u64 v[0:1], s[58:59], 0, v[2:3]
	s_lshl_b32 s58, s74, 20
	s_lshl_b64 s[38:39], s[38:39], 7
	s_add_u32 s38, s58, s38
	s_addc_u32 s39, 0, s39
	v_add_u32_e32 v2, s9, v54
	v_lshl_add_u64 v[4:5], s[38:39], 0, v[2:3]
	v_mov_b32_e32 v14, v3
	v_mov_b32_e32 v15, v3
	v_lshl_add_u64 v[212:213], s[34:35], 0, v[0:1]
	v_lshl_add_u64 v[214:215], s[44:45], 0, v[4:5]
	v_lshl_add_u64 v[216:217], s[46:47], 0, v[0:1]
	v_lshl_add_u64 v[218:219], s[40:41], 0, v[4:5]
	v_mov_b32_e32 v0, v3
	v_mov_b32_e32 v1, v3
	v_mov_b32_e32 v2, v3
	v_mov_b32_e32 v4, v3
	v_mov_b32_e32 v5, v3
	v_mov_b32_e32 v6, v3
	v_mov_b32_e32 v7, v3
	v_mov_b32_e32 v8, v3
	v_mov_b32_e32 v9, v3
	v_mov_b32_e32 v10, v3
	v_mov_b32_e32 v11, v3
	v_mov_b32_e32 v12, v3
	v_mov_b32_e32 v13, v3
	v_mov_b64_e32 v[66:67], v[14:15]
	v_mov_b64_e32 v[50:51], v[14:15]
	v_mov_b64_e32 v[34:35], v[14:15]
	v_mov_b64_e32 v[64:65], v[12:13]
	v_mov_b64_e32 v[62:63], v[10:11]
	v_mov_b64_e32 v[60:61], v[8:9]
	v_mov_b64_e32 v[58:59], v[6:7]
	v_mov_b64_e32 v[56:57], v[4:5]
	v_mov_b64_e32 v[54:55], v[2:3]
	v_mov_b64_e32 v[52:53], v[0:1]
	v_mov_b64_e32 v[48:49], v[12:13]
	v_mov_b64_e32 v[46:47], v[10:11]
	v_mov_b64_e32 v[44:45], v[8:9]
	v_mov_b64_e32 v[42:43], v[6:7]
	v_mov_b64_e32 v[40:41], v[4:5]
	v_mov_b64_e32 v[38:39], v[2:3]
	v_mov_b64_e32 v[36:37], v[0:1]
	v_mov_b64_e32 v[32:33], v[12:13]
	v_mov_b64_e32 v[30:31], v[10:11]
	v_mov_b64_e32 v[28:29], v[8:9]
	v_mov_b64_e32 v[26:27], v[6:7]
	v_mov_b64_e32 v[24:25], v[4:5]
	v_mov_b64_e32 v[22:23], v[2:3]
	v_mov_b64_e32 v[20:21], v[0:1]
	v_mov_b64_e32 v[18:19], v[14:15]
	v_mov_b32_e32 v69, v68
	v_mov_b32_e32 v70, v68
	v_mov_b32_e32 v71, v68
	v_mov_b32_e32 v72, v68
	v_mov_b32_e32 v73, v68
	v_mov_b32_e32 v74, v68
	v_mov_b32_e32 v75, v68
	v_mov_b32_e32 v76, v68
	v_mov_b32_e32 v77, v68
	v_mov_b32_e32 v78, v68
	v_mov_b32_e32 v79, v68
	v_mov_b32_e32 v80, v68
	v_mov_b32_e32 v81, v68
	v_mov_b32_e32 v82, v68
	v_mov_b32_e32 v83, v68
	v_lshl_add_u32 v228, v220, 2, s7
	v_lshlrev_b32_e32 v227, 4, v221
	s_mov_b32 s2, 7
	v_mov_b32_e32 v241, 1.0
	v_mov_b32_e32 v229, 0
	s_mov_b32 s62, 1
	v_mov_b64_e32 v[16:17], v[12:13]
	v_mov_b64_e32 v[14:15], v[10:11]
	v_mov_b64_e32 v[12:13], v[8:9]
	v_mov_b64_e32 v[10:11], v[6:7]
	v_mov_b64_e32 v[8:9], v[4:5]
	v_mov_b64_e32 v[6:7], v[2:3]
	v_mov_b64_e32 v[4:5], v[0:1]
	s_movk_i32 s74, 0x3000
	.p2align 6
	s_mov_b32 s98, 0
	s_waitcnt lgkmcnt(0)
	v_mfma_f32_32x32x64_f8f6f4 v[132:147], v[116:123], v[148:155], v[68:83]
.LBB0_650:
	v_sub_co_u32_e64 v0, s[38:39], s62, 1
	s_and_b64 s[38:39], s[38:39], exec
	v_readfirstlane_b32 s9, v0
	s_cselect_b32 s60, 5, s9
	s_mov_b32 s99, s32
	s_mov_b32 s32, s60
	s_add_i32 s9, s62, 1
	s_cmp_lg_u32 s62, 5
	s_cselect_b32 s9, s9, 0
	s_lshl_b32 s61, s60, 13
	v_add_u32_e32 v2, s61, v239
	v_add_u32_e32 v250, s61, v240
	v_lshl_add_u32 v0, s62, 12, v238
	v_add_u32_e32 v1, v0, v231
	v_add_u32_e32 v0, v0, v232
	ds_read_b128 v[242:245], v1
	ds_read_b128 v[202:205], v1 offset:2048
	ds_read_b128 v[246:249], v0
	ds_read_b128 v[206:209], v0 offset:2048
	v_exp_f32_e32 v100, v100
	v_exp_f32_e32 v101, v101
	v_exp_f32_e32 v102, v102
	v_exp_f32_e32 v103, v103
	v_exp_f32_e32 v104, v104
	v_exp_f32_e32 v105, v105
	v_exp_f32_e32 v106, v106
	v_exp_f32_e32 v107, v107
	v_pk_add_f32 v[0:1], v[100:101], v[102:103]
	v_pk_add_f32 v[252:253], v[104:105], v[106:107]
	v_mfma_f32_32x32x64_f8f6f4 v[116:131], v[188:195], v[148:155], v[68:83]
	s_cmp_eq_u32 s98, 0
	s_cbranch_scc1 .Lattn_dma_done
	s_add_i32 s58, s2, -3
	s_cmp_ge_u32 s58, s92
	s_cbranch_scc1 .Lattn_xdone
	s_lshl_b32 s58, s99, 13
	s_add_i32 s58, s8, s58
	v_lshl_add_u64 v[196:197], v[218:219], 0, s[96:97]
	s_mov_b32 m0, s58
	s_andn2_b64 vcc, exec, s[28:29]
	global_load_lds_dwordx4 v[196:197], off
	v_lshl_add_u64 v[196:197], v[216:217], 0, s[96:97]
	s_add_i32 m0, s58, 0xc000
	s_nop 0
	global_load_lds_dwordx4 v[196:197], off
	s_cbranch_vccnz .Lattn_xdone
	s_mov_b32 s100, 0xfffff000
	s_mov_b32 s101, -1
	s_lshl_b32 s59, s99, 12
	v_lshl_add_u64 v[196:197], v[210:211], 0, s[100:101]
	s_add_i32 m0, s57, s59
	s_nop 0
	global_load_lds_dwordx4 v[196:197], off
.Lattn_xdone:
	s_add_i32 s58, s2, -2
	s_cmp_ge_u32 s58, s92
	s_cbranch_scc1 .Lattn_ydone
	s_add_i32 s58, s8, s64
	v_lshl_add_u64 v[196:197], v[214:215], 0, s[96:97]
	s_mov_b32 m0, s58
	s_andn2_b64 vcc, exec, s[28:29]
	global_load_lds_dwordx4 v[196:197], off
	v_lshl_add_u64 v[196:197], v[212:213], 0, s[96:97]
	s_add_i32 m0, s58, 0xc000
	s_nop 0
	global_load_lds_dwordx4 v[196:197], off
	s_cbranch_vccnz .Lattn_ydone
	s_lshl_b32 s59, s63, 12
	s_add_i32 m0, s57, s59
	s_nop 0
	global_load_lds_dwordx4 v[210:211], off
.Lattn_ydone:
	v_lshl_add_u64 v[210:211], v[210:211], 0, s[22:23]
	v_lshl_add_u64 v[212:213], v[212:213], 0, s[16:17]
	v_lshl_add_u64 v[214:215], v[214:215], 0, s[12:13]
	v_lshl_add_u64 v[216:217], v[216:217], 0, s[16:17]
	v_lshl_add_u64 v[218:219], v[218:219], 0, s[12:13]
.Lattn_dma_done:
	v_exp_f32_e32 v108, v108
	v_exp_f32_e32 v109, v109
	v_exp_f32_e32 v110, v110
	v_exp_f32_e32 v111, v111
	v_exp_f32_e32 v112, v112
	v_exp_f32_e32 v113, v113
	v_exp_f32_e32 v114, v114
	v_exp_f32_e32 v115, v115
	v_pk_add_f32 v[0:1], v[108:109], v[0:1]
	v_pk_add_f32 v[252:253], v[252:253], v[110:111]
	v_pk_add_f32 v[0:1], v[112:113], v[0:1]
	v_pk_add_f32 v[252:253], v[252:253], v[114:115]
	v_mfma_f32_32x32x64_f8f6f4 v[132:147], v[180:187], v[156:163], v[132:147]
	v_exp_f32_e32 v84, v84
	v_exp_f32_e32 v85, v85
	v_exp_f32_e32 v86, v86
	v_exp_f32_e32 v87, v87
	v_exp_f32_e32 v88, v88
	v_exp_f32_e32 v89, v89
	v_exp_f32_e32 v90, v90
	v_exp_f32_e32 v91, v91
	v_pk_add_f32 v[0:1], v[84:85], v[0:1]
	v_pk_add_f32 v[252:253], v[252:253], v[86:87]
	v_pk_add_f32 v[0:1], v[88:89], v[0:1]
	v_pk_add_f32 v[252:253], v[252:253], v[90:91]
	v_mfma_f32_32x32x64_f8f6f4 v[116:131], v[172:179], v[156:163], v[116:131]
	ds_read_b64 v[182:183], v250
	ds_read_b64 v[176:177], v250 offset:2048
	ds_read_b128 v[178:181], v2
	ds_read_b128 v[172:175], v2 offset:2048
	v_exp_f32_e32 v92, v92
	v_exp_f32_e32 v93, v93
	v_exp_f32_e32 v94, v94
	v_exp_f32_e32 v95, v95
	v_exp_f32_e32 v96, v96
	v_exp_f32_e32 v97, v97
	v_exp_f32_e32 v98, v98
	v_exp_f32_e32 v99, v99
	v_pk_add_f32 v[0:1], v[92:93], v[0:1]
	v_pk_add_f32 v[252:253], v[252:253], v[94:95]
	v_pk_add_f32 v[0:1], v[96:97], v[0:1]
	v_pk_add_f32 v[252:253], v[252:253], v[98:99]
	v_cvt_scalef32_2xpk16_bf6_f32 v[196:201], v[100:115], v[84:99], 1.0
	v_pk_add_f32 v[0:1], v[0:1], v[252:253]
	s_waitcnt lgkmcnt(4)
	v_mfma_f32_32x32x64_f8f6f4 v[132:147], v[242:249], v[164:171], v[132:147]
	s_nop 0
	v_pk_add_f32 v[0:1], v[0:1], v[0:1] op_sel:[0,1] op_sel_hi:[1,0]
	s_nop 0
	v_mov_b32_e32 v1, v0
	s_nop 1
	v_permlane32_swap_b32_e32 v0, v1
	v_mfma_f32_32x32x64_f8f6f4 v[116:131], v[202:209], v[164:171], v[116:131]
	s_waitcnt lgkmcnt(0)
	v_mfma_f32_32x32x64_f8f6f4 v[52:67], v[196:201], v[178:183], v[52:67] cbsz:3 blgp:2
	ds_read_b64 v[102:103], v250 offset:4096
	ds_read_b64 v[96:97], v250 offset:6144
	ds_read_b128 v[98:101], v2 offset:4096
	ds_read_b128 v[92:95], v2 offset:6144
	v_max3_f32 v84, v132, v133, v134
	v_max3_f32 v2, v135, v136, v137
	v_max3_f32 v84, v84, v138, v139
	s_nop 0
	v_max3_f32 v2, v2, v140, v141
	v_max3_f32 v84, v84, v142, v143
	s_nop 0
	v_max3_f32 v2, v2, v144, v145
	v_max3_f32 v84, v84, v146, v147
	v_mfma_f32_32x32x64_f8f6f4 v[36:51], v[196:201], v[172:177], v[36:51] cbsz:3 blgp:2
	v_lshl_add_u32 v105, s9, 13, v233
	v_max3_f32 v84, v84, v116, v117
	v_add_u32_e32 v88, v105, v234
	v_add_u32_e32 v106, v105, v235
	v_max3_f32 v104, v84, v120, v121
	ds_read_b128 v[84:87], v88 offset:49152
	ds_read_b128 v[188:191], v88 offset:53248
	ds_read_b128 v[88:91], v106 offset:49152
	ds_read_b128 v[192:195], v106 offset:53248
	v_add_u32_e32 v106, v105, v236
	v_add_u32_e32 v105, v105, v237
	ds_read_b128 v[180:183], v106 offset:49152
	ds_read_b128 v[172:175], v106 offset:53248
	ds_read_b128 v[184:187], v105 offset:49152
	ds_read_b128 v[176:179], v105 offset:53248
	v_max3_f32 v2, v2, v118, v119
	v_max3_f32 v104, v104, v124, v125
	s_nop 0
	v_max3_f32 v2, v2, v122, v123
	v_max3_f32 v104, v104, v128, v129
	s_nop 0
	v_max3_f32 v2, v2, v126, v127
	s_nop 0
	v_max3_f32 v2, v2, v130, v131
	s_waitcnt lgkmcnt(8)
	v_mfma_f32_32x32x64_f8f6f4 v[20:35], v[196:201], v[98:103], v[20:35] cbsz:3 blgp:2
	v_max_f32_e32 v2, v2, v2
	v_max_f32_e32 v98, v104, v104
	v_max_f32_e32 v2, v98, v2
	v_mov_b32_e32 v98, v2
	s_nop 1
	v_permlane32_swap_b32_e32 v2, v98
	v_max_f32_e32 v98, v98, v98
	v_max_f32_e32 v2, v2, v2
	v_max_f32_e32 v2, v2, v98
	v_cmp_ge_f32_e32 vcc, s0, v2
	s_cmp_eq_u64 vcc, exec
	s_cbranch_scc0 .LBB0_683
	v_mov_b32_e32 v242, 1.0

.LBB0_656:
	s_waitcnt lgkmcnt(0)
.LBB0_666:
	v_sub_co_u32_e64 v2, s[60:61], s9, 1
	s_and_b64 s[60:61], s[60:61], exec
	v_readfirstlane_b32 s60, v2
	s_cselect_b32 s63, 5, s60
	s_add_i32 s60, s9, 1
	s_cmp_lg_u32 s9, 5
	s_cselect_b32 s62, s60, 0
	s_lshl_b32 s64, s63, 13
	v_add_u32_e32 v2, s64, v239
	v_add_u32_e32 v243, s64, v240
	v_lshl_add_u32 v92, s9, 12, v238
	v_add_u32_e32 v93, v92, v231
	v_add_u32_e32 v92, v92, v232
	ds_read_b128 v[202:205], v93
	ds_read_b128 v[244:247], v93 offset:2048
	ds_read_b128 v[206:209], v92
	ds_read_b128 v[248:251], v92 offset:2048
	v_mfma_f32_32x32x64_f8f6f4 v[100:115], v[84:91], v[148:155], v[68:83]
	v_exp_f32_e32 v132, v132
	v_exp_f32_e32 v133, v133
	v_exp_f32_e32 v134, v134
	v_exp_f32_e32 v135, v135
	v_exp_f32_e32 v136, v136
	v_exp_f32_e32 v137, v137
	v_exp_f32_e32 v138, v138
	v_exp_f32_e32 v139, v139
	v_pk_add_f32 v[196:197], v[132:133], v[134:135]
	v_pk_add_f32 v[252:253], v[136:137], v[138:139]
	v_mfma_f32_32x32x64_f8f6f4 v[84:99], v[188:195], v[148:155], v[68:83]
	v_exp_f32_e32 v140, v140
	v_exp_f32_e32 v141, v141
	v_exp_f32_e32 v142, v142
	v_exp_f32_e32 v143, v143
	v_exp_f32_e32 v144, v144
	v_exp_f32_e32 v145, v145
	v_exp_f32_e32 v146, v146
	v_exp_f32_e32 v147, v147
	v_pk_add_f32 v[188:189], v[140:141], v[196:197]
	v_pk_add_f32 v[252:253], v[252:253], v[142:143]
	v_pk_add_f32 v[188:189], v[144:145], v[188:189]
	v_pk_add_f32 v[252:253], v[252:253], v[146:147]
	v_mfma_f32_32x32x64_f8f6f4 v[100:115], v[180:187], v[156:163], v[100:115]
	v_exp_f32_e32 v116, v116
	v_exp_f32_e32 v117, v117
	v_exp_f32_e32 v118, v118
	v_exp_f32_e32 v119, v119
	v_exp_f32_e32 v120, v120
	v_exp_f32_e32 v121, v121
	v_exp_f32_e32 v122, v122
	v_exp_f32_e32 v123, v123
	v_pk_add_f32 v[180:181], v[116:117], v[188:189]
	v_pk_add_f32 v[252:253], v[252:253], v[118:119]
	v_pk_add_f32 v[184:185], v[120:121], v[180:181]
	v_pk_add_f32 v[252:253], v[252:253], v[122:123]
	v_mfma_f32_32x32x64_f8f6f4 v[84:99], v[172:179], v[156:163], v[84:99]
	ds_read_b64 v[182:183], v243
	ds_read_b64 v[176:177], v243 offset:2048
	ds_read_b128 v[178:181], v2
	ds_read_b128 v[172:175], v2 offset:2048
	v_exp_f32_e32 v124, v124
	v_exp_f32_e32 v125, v125
	v_exp_f32_e32 v126, v126
	v_exp_f32_e32 v127, v127
	v_exp_f32_e32 v128, v128
	v_exp_f32_e32 v129, v129
	v_exp_f32_e32 v130, v130
	v_exp_f32_e32 v131, v131
	v_pk_add_f32 v[184:185], v[124:125], v[184:185]
	v_pk_add_f32 v[252:253], v[252:253], v[126:127]
	v_pk_add_f32 v[184:185], v[128:129], v[184:185]
	v_pk_add_f32 v[252:253], v[252:253], v[130:131]
	v_cvt_scalef32_2xpk16_bf6_f32 v[196:201], v[132:147], v[116:131], 1.0
	v_pk_add_f32 v[184:185], v[184:185], v[252:253]
	s_waitcnt lgkmcnt(4)
	v_mfma_f32_32x32x64_f8f6f4 v[100:115], v[202:209], v[164:171], v[100:115]
	s_nop 0
	v_pk_add_f32 v[130:131], v[184:185], v[184:185] op_sel:[0,1] op_sel_hi:[1,0]
	s_nop 0
	v_mov_b32_e32 v131, v130
	s_nop 1
	v_permlane32_swap_b32_e32 v130, v131
	v_mfma_f32_32x32x64_f8f6f4 v[84:99], v[244:251], v[164:171], v[84:99]
	s_waitcnt lgkmcnt(0)
	v_mfma_f32_32x32x64_f8f6f4 v[52:67], v[196:201], v[178:183], v[52:67] cbsz:3 blgp:2
	ds_read_b64 v[136:137], v243 offset:4096
	ds_read_b64 v[128:129], v243 offset:6144
	ds_read_b128 v[132:135], v2 offset:4096
	ds_read_b128 v[124:127], v2 offset:6144
	v_max3_f32 v116, v100, v101, v102
	v_max3_f32 v2, v103, v104, v105
	v_max3_f32 v116, v116, v106, v107
	s_nop 0
	v_max3_f32 v2, v2, v108, v109
	v_max3_f32 v116, v116, v110, v111
	s_nop 0
	v_max3_f32 v2, v2, v112, v113
	v_max3_f32 v116, v116, v114, v115
	v_mfma_f32_32x32x64_f8f6f4 v[36:51], v[196:201], v[172:177], v[36:51] cbsz:3 blgp:2
	s_lshl_b32 s9, s62, 13
	v_add_u32_e32 v139, s9, v233
	v_max3_f32 v116, v116, v84, v85
	v_add_u32_e32 v120, v139, v234
	v_add_u32_e32 v140, v139, v235
	v_max3_f32 v138, v116, v88, v89
	ds_read_b128 v[116:119], v120 offset:49152
	ds_read_b128 v[188:191], v120 offset:53248
	ds_read_b128 v[120:123], v140 offset:49152
	ds_read_b128 v[192:195], v140 offset:53248
	v_add_u32_e32 v140, v139, v236
	v_add_u32_e32 v139, v139, v237
	ds_read_b128 v[180:183], v140 offset:49152
	ds_read_b128 v[172:175], v140 offset:53248
	ds_read_b128 v[184:187], v139 offset:49152
	ds_read_b128 v[176:179], v139 offset:53248
	v_max3_f32 v2, v2, v86, v87
	v_max3_f32 v138, v138, v92, v93
	s_nop 0
	v_max3_f32 v2, v2, v90, v91
	v_max3_f32 v138, v138, v96, v97
	s_nop 0
	v_max3_f32 v2, v2, v94, v95
	s_nop 0
	v_max3_f32 v2, v2, v98, v99
	s_waitcnt lgkmcnt(8)
	v_mfma_f32_32x32x64_f8f6f4 v[20:35], v[196:201], v[132:137], v[20:35] cbsz:3 blgp:2
	v_max_f32_e32 v2, v2, v2
	v_max_f32_e32 v132, v138, v138
	v_max_f32_e32 v2, v132, v2
	v_mov_b32_e32 v132, v2
	s_nop 1
	v_permlane32_swap_b32_e32 v2, v132
	v_max_f32_e32 v132, v132, v132
	v_max_f32_e32 v2, v2, v2
	v_max_f32_e32 v132, v2, v132
	v_cmp_ge_f32_e32 vcc, s0, v132
	s_cmp_eq_u64 vcc, exec
	v_mov_b32_e32 v2, 1.0
	s_cbranch_scc0 .LBB0_684

; #define SBAR() __builtin_amdgcn_sched_barrier(0)
; #define ATT_MFMA_SETTLE() asm volatile("s_nop 15\n\ts_nop 15" ::: "memory")
; #define ATT_BAR() asm volatile("s_waitcnt lgkmcnt(0)\n\ts_barrier" ::: "memory")
; #define ATT_WAITV(n) asm volatile("s_waitcnt vmcnt(" #n ")" ::: "memory")
; #define KLOAD(sl_) k_load_nope(k0, k1, KN_lds + (sl_) * SHM_KN, r32, hi)
; #define WAIT_TILES2() do { if (wid < 4) { ATT_WAITV(6); } else { ATT_WAITV(4); } } while (0)
; __device__ __forceinline__ void attn_unit(const bf16_t* __restrict__ Qb, const unsigned char* __restrict__ Kn, const unsigned char* __restrict__ Vp, const unsigned char* __restrict__ Kp, ...
;     ...
;   ISSUE(0, 0); ISSUE(1, KVBLK); ISSUE(2, 2 * KVBLK); ISSUE(3, 3 * KVBLK); ISSUE(4, 4 * KVBLK);
;   if (wid < 4) { ATT_WAITV(9); } else { ATT_WAITV(6); }
;   ATT_BAR();
;   KLOAD(0); qk_mma(pA0, pA1, k0, k1, KR_lds, qf, nm, r32, hi, sc); ATT_MFMA_SETTLE(); SBAR(); KLOAD(1); partialSM(pA0, pA1, nm, alA, true);
;   WAIT_TILES2(); ATT_BAR();
;   ISSUE(5, 5 * KVBLK);
;   int s0 = 1;
;   for (int j = 1; j + 1 < NT; j += 2) {
;     STEP(j, pB0, pB1, alB, pA0, pA1, alA);
;     STEP(j + 1, pA0, pA1, alA, pB0, pB1, alB);
;   }
.LBB0_681:
	v_add_f32_e32 v0, v0, v1
	v_fmac_f32_e32 v0, v229, v241
	v_add_f32_e32 v229, v130, v131
	s_add_i32 s59, s2, 2
	s_add_i32 s2, s2, -3
	v_fmac_f32_e32 v229, v0, v242
	s_cmp_ge_u32 s2, s92
	s_cbranch_scc1 .LBB0_685
	s_mov_b32 s2, s59
	v_mov_b32_e32 v241, v2
	s_mov_b32 s98, 1
	s_branch .LBB0_650
